# all: v24 attention + mLSTM chains with rotating fragment registers + mLSTM prefetch loads spread over step 2 + small_gemm fragment loads issued up front
# speedup vs baseline: 1.0112x; 1.0051x over previous
; DI unsigned pk2(float a, float b) { f32x2 v = {a, b}; hbf2 r = __builtin_convertvector(v, hbf2); return __builtin_bit_cast(unsigned, r); }
; DI float sigmoidf_(float x) { return __builtin_amdgcn_rcpf(1.0f + __expf(-x)); }
; DI float gelu_tanh(float x) { const float z = 1.5957691216057308f * (x + 0.044715f * x * x * x); return x * sigmoidf_(z); }
; DI int tid_fresh() { int t = threadIdx.x; asm volatile("" : "+v"(t)); return t; }
; DI f32x4 mfma16(bf16x8 a, bf16x8 b, f32x4 c) { return __builtin_amdgcn_mfma_f32_16x16x32_bf16(a, b, c, 0, 0, 0); }
; template <class Epi> DI void small_gemm(const bf16_t* A, const bf16_t* Bt, int N, int K, const Epi& E) {
;     const int tid = tid_fresh(), lane = tid & 63, wid = tid >> 6, fr = lane & 15, fq = lane >> 4;
;     const int nw = gridDim.x * 8;
;     for (int tile = blockIdx.x * 8 + wid; tile < (N >> 4); tile += nw) {
;         const int n0 = tile * 16;
;         f32x4 acc = (f32x4){0.f, 0.f, 0.f, 0.f};
;         const bf16_t* ap = A + (size_t)fr * K + fq * 8;
;         const bf16_t* bp = Bt + (size_t)(n0 + fr) * K + fq * 8;
; #pragma unroll 16
;         for (int k = 0; k < K; k += 32) acc = mfma16(*(const bf16x8*)(bp + k), *(const bf16x8*)(ap + k), acc);
;         E(acc, fr, n0 + fq * 4, fq);
;     }
; }
;     DI void operator()(f32x4 v, int row, int n, int fq) const {
;         bf16_t* dst;
;         if (n < 4096) dst = T1 + (size_t)(MR + row) * 4096 + n;
;         else {
;             dst = OG + (size_t)(MR + row) * 2048 + (n - 4096);
;             if (n < 5120) {
; #pragma unroll
;                 for (int j = 0; j < 4; ++j) v[j] = sigmoidf_(v[j]);
;             } else {
; #pragma unroll
;                 for (int j = 0; j < 4; ++j) v[j] = gelu_tanh(v[j]);
;             }
;         }
;         u32x2 w; w.x = pk2(v[0], v[1]); w.y = pk2(v[2], v[3]);
;         *(u32x2*)dst = w;
.LBB0_150:
	v_lshl_add_u64 v[84:85], v[18:19], 0, v[10:11]
	v_add_co_u32_e32 v92, vcc, 0x7ac7000, v84
	v_lshl_add_u64 v[20:21], v[16:17], 0, v[10:11]
	s_nop 0
	v_addc_co_u32_e32 v93, vcc, 0, v85, vcc
	global_load_dwordx4 v[24:27], v[20:21], off
	global_load_dwordx4 v[100:103], v[92:93], off offset:2816
	global_load_dwordx4 v[28:31], v[20:21], off offset:64
	global_load_dwordx4 v[104:107], v[92:93], off offset:2880
	global_load_dwordx4 v[32:35], v[20:21], off offset:128
	global_load_dwordx4 v[108:111], v[92:93], off offset:2944
	global_load_dwordx4 v[36:39], v[20:21], off offset:192
	global_load_dwordx4 v[112:115], v[92:93], off offset:3008
	global_load_dwordx4 v[40:43], v[20:21], off offset:256
	global_load_dwordx4 v[116:119], v[92:93], off offset:3072
	global_load_dwordx4 v[44:47], v[20:21], off offset:320
	global_load_dwordx4 v[120:123], v[92:93], off offset:3136
	global_load_dwordx4 v[48:51], v[20:21], off offset:384
	global_load_dwordx4 v[124:127], v[92:93], off offset:3200
	global_load_dwordx4 v[52:55], v[20:21], off offset:448
	global_load_dwordx4 v[128:131], v[92:93], off offset:3264
	global_load_dwordx4 v[56:59], v[20:21], off offset:512
	global_load_dwordx4 v[132:135], v[92:93], off offset:3328
	global_load_dwordx4 v[60:63], v[20:21], off offset:576
	global_load_dwordx4 v[136:139], v[92:93], off offset:3392
	global_load_dwordx4 v[64:67], v[20:21], off offset:640
	global_load_dwordx4 v[140:143], v[92:93], off offset:3456
	global_load_dwordx4 v[68:71], v[20:21], off offset:704
	global_load_dwordx4 v[144:147], v[92:93], off offset:3520
	global_load_dwordx4 v[72:75], v[20:21], off offset:768
	global_load_dwordx4 v[148:151], v[92:93], off offset:3584
	global_load_dwordx4 v[76:79], v[20:21], off offset:832
	global_load_dwordx4 v[152:155], v[92:93], off offset:3648
	global_load_dwordx4 v[80:83], v[20:21], off offset:896
	global_load_dwordx4 v[156:159], v[92:93], off offset:3712
	global_load_dwordx4 v[164:167], v[20:21], off offset:960
	global_load_dwordx4 v[160:163], v[92:93], off offset:3776
	s_addk_i32 s10, 0x200
	v_lshl_add_u64 v[18:19], v[18:19], 0, s[6:7]
	s_cmpk_gt_u32 s10, 0x3df
	v_lshl_add_u64 v[16:17], v[16:17], 0, s[6:7]
	s_waitcnt vmcnt(30)
	v_mfma_f32_16x16x32_bf16 v[0:3], v[24:27], v[100:103], v[0:3]
	s_waitcnt vmcnt(28)
	v_mfma_f32_16x16x32_bf16 v[0:3], v[28:31], v[104:107], v[0:3]
	s_waitcnt vmcnt(26)
	v_mfma_f32_16x16x32_bf16 v[0:3], v[32:35], v[108:111], v[0:3]
	s_waitcnt vmcnt(24)
	v_mfma_f32_16x16x32_bf16 v[0:3], v[36:39], v[112:115], v[0:3]
	s_waitcnt vmcnt(22)
	v_mfma_f32_16x16x32_bf16 v[0:3], v[40:43], v[116:119], v[0:3]
	s_waitcnt vmcnt(20)
	v_mfma_f32_16x16x32_bf16 v[0:3], v[44:47], v[120:123], v[0:3]
	s_waitcnt vmcnt(18)
	v_mfma_f32_16x16x32_bf16 v[0:3], v[48:51], v[124:127], v[0:3]
	s_waitcnt vmcnt(16)
	v_mfma_f32_16x16x32_bf16 v[0:3], v[52:55], v[128:131], v[0:3]
	s_waitcnt vmcnt(14)
	v_mfma_f32_16x16x32_bf16 v[0:3], v[56:59], v[132:135], v[0:3]
	s_waitcnt vmcnt(12)
	v_mfma_f32_16x16x32_bf16 v[0:3], v[60:63], v[136:139], v[0:3]
	s_waitcnt vmcnt(10)
	v_mfma_f32_16x16x32_bf16 v[0:3], v[64:67], v[140:143], v[0:3]
	s_waitcnt vmcnt(8)
	v_mfma_f32_16x16x32_bf16 v[0:3], v[68:71], v[144:147], v[0:3]
	s_waitcnt vmcnt(6)
	v_mfma_f32_16x16x32_bf16 v[0:3], v[72:75], v[148:151], v[0:3]
	s_waitcnt vmcnt(4)
	v_mfma_f32_16x16x32_bf16 v[0:3], v[76:79], v[152:155], v[0:3]
	s_waitcnt vmcnt(2)
	v_mfma_f32_16x16x32_bf16 v[0:3], v[80:83], v[156:159], v[0:3]
	s_waitcnt vmcnt(0)
	v_mfma_f32_16x16x32_bf16 v[0:3], v[164:167], v[160:163], v[0:3]
	s_cbranch_scc0 .LBB0_150
	v_lshlrev_b32_e32 v15, 4, v22
	v_or_b32_e32 v4, v15, v23
	v_cmp_lt_i32_e32 vcc, s3, v4
	s_and_saveexec_b64 s[10:11], vcc
	s_xor_b64 s[10:11], exec, s[10:11]
	s_cbranch_execz .LBB0_157
	v_cmp_lt_u32_e32 vcc, s14, v15
	s_and_saveexec_b64 s[12:13], vcc
	s_xor_b64 s[12:13], exec, s[12:13]
	s_cbranch_execz .LBB0_154
	v_mul_f32_e32 v15, 0x3d372713, v0
	v_mul_f32_e32 v15, v0, v15
	v_fma_f32 v15, v0, v15, v0
	v_mul_f32_e32 v15, 0x3fcc422a, v15
	v_mul_f32_e32 v15, 0xbfb8aa3b, v15
	v_exp_f32_e32 v15, v15
	v_mul_f32_e32 v16, 0x3d372713, v1
	v_mul_f32_e32 v16, v1, v16
	v_fma_f32 v17, v1, v16, v1
	v_add_f32_e32 v15, 1.0, v15
	v_rcp_f32_e32 v16, v15
	v_mul_f32_e32 v15, 0x3fcc422a, v17
	v_mul_f32_e32 v17, 0x3d372713, v2
	v_mul_f32_e32 v17, v2, v17
	v_mul_f32_e32 v18, 0x3d372713, v3
	v_fma_f32 v17, v2, v17, v2
	v_mul_f32_e32 v18, v3, v18
	v_mul_f32_e32 v17, 0x3fcc422a, v17
	v_fma_f32 v18, v3, v18, v3
	v_mul_f32_e32 v17, 0xbfb8aa3b, v17
	v_mul_f32_e32 v18, 0x3fcc422a, v18
	v_mul_f32_e32 v15, 0xbfb8aa3b, v15
	v_exp_f32_e32 v17, v17
	v_mul_f32_e32 v18, 0xbfb8aa3b, v18
	v_exp_f32_e32 v15, v15
	v_exp_f32_e32 v19, v18
	v_add_f32_e32 v17, 1.0, v17
	v_rcp_f32_e32 v18, v17
	v_add_f32_e32 v15, 1.0, v15
	v_add_f32_e32 v17, 1.0, v19
	v_rcp_f32_e32 v19, v17
	v_rcp_f32_e32 v17, v15
	v_pk_mul_f32 v[18:19], v[2:3], v[18:19]
	v_pk_mul_f32 v[16:17], v[0:1], v[16:17]

; DI unsigned pk2(float a, float b) { f32x2 v = {a, b}; hbf2 r = __builtin_convertvector(v, hbf2); return __builtin_bit_cast(unsigned, r); }
; DI void mlstm_unit(const Params& p, unsigned char* smem, int unit) {
;     ...
;     auto issue_loads = [&](int c) __attribute__((always_inline)) {
;         const int base = c == 0 ? MR : b * 4096 + (c - 1) * 64;
;         const int nv = c == 0 ? 16 : 64;
; #pragma unroll
;         for (int i = 0; i < 4; ++i) {
;             const int vid = tid + 512 * i, s = vid >> 5, kv = vid & 31;
;             const size_t row = (size_t)(base + (s < nv ? s : nv - 1));
;             rq[i] = *(const u32x4*)(T1 + row * 4096 + h * 256 + kv * 8);
;             rk[i] = *(const u32x4*)(T1 + row * 4096 + 1024 + h * 256 + kv * 8);
;         }
;         {
;             const int s = lane, vv = wid;
;             const size_t row = (size_t)(base + (s < nv ? s : nv - 1));
;             rv = *(const u32x4*)(T1 + row * 4096 + 2048 + h * 256 + sl * 64 + vv * 8);
;         }
;         if (wid == 0) {
;             const bool ok = lane < nv;
;             const int row = base + (ok ? lane : 0);
;             rli = ok ? LI[row * 4 + h] : -1e30f;
;             rlf = ok ? LF[row * 4 + h] : 0.f;
;         }
;     ...
; #pragma unroll
;         for (int a = 0; a < 2; ++a)
; #pragma unroll
;             for (int v = 0; v < 4; ++v) {
;                 u32x2 w; w.x = pk2(accC[a][v][0], accC[a][v][1]); w.y = pk2(accC[a][v][2], accC[a][v][3]);
;                 *(u32x2*)(sCb + (v * 16 + fr) * 264 + (2 * wid + a) * 16 + fq * 4) = w;
;             }
; #pragma unroll
;         for (int i = 0; i < 4; ++i) {
;             const int vid = tid + 512 * i, s = vid >> 5, kv = vid & 31;
;             *(u32x4*)(sQ + s * 264 + kv * 8) = rq[i];
;             *(u32x4*)(sK + s * 264 + kv * 8) = rk[i];
;         }
;         {
;             const int s = lane, vv = wid;
;             const unsigned wv[4] = {rv.x, rv.y, rv.z, rv.w};
; #pragma unroll
;             for (int e = 0; e < 4; ++e) {
;                 sVt[(vv * 8 + 2 * e) * 72 + s] = (bf16_t)(wv[e] & 0xffffu);
;                 sVt[(vv * 8 + 2 * e + 1) * 72 + s] = (bf16_t)(wv[e] >> 16);
;             }
;         }
;         __syncthreads();
;         const u32x2 og0 = rog[0], og1 = rog[1];
;         if (c + 1 < 65) issue_loads(c + 1);
.LBB0_376:
	v_cvt_pk_bf16_f32 v68, v36, v37
	v_cvt_pk_bf16_f32 v69, v38, v39
	v_cvt_pk_bf16_f32 v76, v48, v49
	v_cvt_pk_bf16_f32 v77, v50, v51
	v_cvt_pk_bf16_f32 v70, v40, v41
	v_cvt_pk_bf16_f32 v71, v42, v43
	ds_write2_b64 v189, v[68:69], v[76:77] offset1:4
	v_cvt_pk_bf16_f32 v68, v52, v53
	v_cvt_pk_bf16_f32 v69, v54, v55
	v_add_u32_e32 v76, 0x2000, v189
	s_cmpk_eq_i32 s97, 0x1000
	v_cvt_pk_bf16_f32 v72, v44, v45
	v_cvt_pk_bf16_f32 v73, v46, v47
	ds_write2_b64 v76, v[70:71], v[68:69] offset0:32 offset1:36
	v_cvt_pk_bf16_f32 v68, v56, v57
	v_cvt_pk_bf16_f32 v69, v58, v59
	v_add_u32_e32 v70, 0x4000, v189
	s_cselect_b64 s[76:77], -1, 0
	v_cvt_pk_bf16_f32 v74, v64, v65
	v_cvt_pk_bf16_f32 v75, v66, v67
	ds_write2_b64 v70, v[72:73], v[68:69] offset0:64 offset1:68
	v_cvt_pk_bf16_f32 v68, v60, v61
	v_cvt_pk_bf16_f32 v69, v62, v63
	v_add_u32_e32 v70, 0x6000, v189
	s_and_b64 vcc, exec, s[76:77]
	ds_write2_b64 v70, v[74:75], v[68:69] offset0:96 offset1:100
	s_waitcnt vmcnt(10)
	ds_write_b128 v110, v[0:3]
	s_waitcnt vmcnt(9)
	ds_write_b128 v110, v[4:7] offset:33792
	s_waitcnt vmcnt(8)
	ds_write_b128 v112, v[8:11]
	s_waitcnt vmcnt(7)
	ds_write_b128 v112, v[12:15] offset:33792
	s_waitcnt vmcnt(6)
	ds_write_b128 v114, v[16:19]
	s_waitcnt vmcnt(5)
	ds_write_b128 v114, v[20:23] offset:33792
	s_waitcnt vmcnt(4)
	ds_write_b128 v116, v[24:27]
	s_waitcnt vmcnt(3)
	ds_write_b128 v116, v[28:31] offset:33792
	s_waitcnt vmcnt(2)
	ds_write_b16 v111, v32
	ds_write_b16_d16_hi v113, v32 offset:144
	ds_write_b16 v111, v33 offset:288
	ds_write_b16_d16_hi v115, v33 offset:144
	ds_write_b16 v111, v34 offset:576
	ds_write_b16_d16_hi v117, v34 offset:144
	ds_write_b16 v111, v35 offset:864
	ds_write_b16_d16_hi v159, v35 offset:144
	s_waitcnt lgkmcnt(0)
	s_barrier
	s_cbranch_vccnz .LBB0_380
	v_add_u32_e32 v32, s97, v184
	v_ashrrev_i32_e32 v33, 31, v32
	v_lshlrev_b64 v[32:33], 13, v[32:33]
	v_lshl_add_u64 v[32:33], s[66:67], 0, v[32:33]
	v_lshl_add_u64 v[32:33], v[32:33], 0, s[92:93]
	s_mov_b32 s39, s93
	v_add_u32_e32 v0, s97, v188
	v_add_u32_e32 v8, s97, v187
	v_add_u32_e32 v16, s97, v186
	v_add_u32_e32 v24, s97, v185
	v_lshl_add_u64 v[32:33], v[32:33], 0, s[38:39]
	v_ashrrev_i32_e32 v1, 31, v0
	v_ashrrev_i32_e32 v9, 31, v8
	v_ashrrev_i32_e32 v17, 31, v16
	v_ashrrev_i32_e32 v25, 31, v24
	v_lshl_add_u64 v[32:33], v[106:107], 1, v[32:33]
	v_lshlrev_b64 v[0:1], 13, v[0:1]
	v_lshlrev_b64 v[8:9], 13, v[8:9]
	v_lshlrev_b64 v[16:17], 13, v[16:17]
	v_lshlrev_b64 v[24:25], 13, v[24:25]
	v_add_co_u32_e32 v32, vcc, 0x1000, v32
	v_lshl_add_u64 v[4:5], v[120:121], 0, v[0:1]
	v_lshl_add_u64 v[12:13], v[120:121], 0, v[8:9]
	v_lshl_add_u64 v[20:21], v[120:121], 0, v[16:17]
	v_lshl_add_u64 v[28:29], v[120:121], 0, v[24:25]
	v_addc_co_u32_e32 v33, vcc, 0, v33, vcc
	s_and_saveexec_b64 s[72:73], s[6:7]
	s_cbranch_execz .LBB0_379
	v_ashrrev_i32_e32 v125, 31, v124
	v_lshlrev_b64 v[68:69], 2, v[124:125]
	v_lshl_add_u64 v[70:71], s[80:81], 0, v[68:69]
	v_lshl_add_u64 v[68:69], s[36:37], 0, v[68:69]
	global_load_dword v125, v[70:71], off
	global_load_dword v143, v[68:69], off

; DI unsigned pk2(float a, float b) { f32x2 v = {a, b}; hbf2 r = __builtin_convertvector(v, hbf2); return __builtin_bit_cast(unsigned, r); }
; DI float bf2f(bf16_t b) { return __uint_as_float(((unsigned)b) << 16); }
; DI void mlstm_unit(const Params& p, unsigned char* smem, int unit) {
;     ...
;         for (int i = 0; i < 4; ++i) {
;             const int vid = tid + 512 * i, s = vid >> 5, kv = vid & 31;
;             const size_t row = (size_t)(base + (s < nv ? s : nv - 1));
;             rq[i] = *(const u32x4*)(T1 + row * 4096 + h * 256 + kv * 8);
;             rk[i] = *(const u32x4*)(T1 + row * 4096 + 1024 + h * 256 + kv * 8);
;         }
;     ...
; #pragma unroll
;         for (int i = 0; i < 4; ++i) {
;             const int task = tid + 512 * i, k = task & 255, s0 = (task >> 8) * 8;
;             float v[8];
;             const f32x4 wa = *(const f32x4*)(sws + s0), wb = *(const f32x4*)(sws + s0 + 4);
; #pragma unroll
;             for (int e = 0; e < 4; ++e) { v[e] = bf2f(sK[(s0 + e) * 264 + k]) * wa[e]; v[4 + e] = bf2f(sK[(s0 + 4 + e) * 264 + k]) * wb[e]; }
;             u32x4 w; w.x = pk2(v[0], v[1]); w.y = pk2(v[2], v[3]); w.z = pk2(v[4], v[5]); w.w = pk2(v[6], v[7]);
;             *(u32x4*)(sKwt + k * 72 + s0) = w;
;         }
.LBB0_381:
	s_and_b32 s39, 1, s96
	s_cselect_b32 s72, 0, 0x540
	s_add_i32 s82, s72, 0
	s_add_i32 s82, s82, 0x26800
	v_lshl_add_u32 v72, v160, 2, s82
	ds_read_b128 v[68:71], v72 offset:1024
	ds_read_b128 v[72:75], v72 offset:1040
	ds_read_u16 v76, v161 offset:33792
	ds_read_u16 v77, v161 offset:34320
	ds_read_u16 v78, v162 offset:35904
	ds_read_u16 v79, v162 offset:36432
	ds_read_u16 v80, v161 offset:34848
	ds_read_u16 v81, v162 offset:36960
	ds_read_u16 v82, v162 offset:37488
	ds_read_u16 v83, v161 offset:35376
	s_waitcnt lgkmcnt(6)
	v_lshlrev_b32_e32 v77, 16, v77
	v_lshlrev_b32_e32 v76, 16, v76
	v_pk_mul_f32 v[68:69], v[68:69], v[76:77]
	s_waitcnt lgkmcnt(4)
	v_lshlrev_b32_e32 v77, 16, v79
	v_lshlrev_b32_e32 v76, 16, v78
	v_pk_mul_f32 v[72:73], v[72:73], v[76:77]
	s_waitcnt lgkmcnt(0)
	v_lshlrev_b32_e32 v77, 16, v83
	v_lshlrev_b32_e32 v76, 16, v80
	v_pk_mul_f32 v[70:71], v[70:71], v[76:77]
	v_lshlrev_b32_e32 v77, 16, v82
	v_lshlrev_b32_e32 v76, 16, v81
	v_pk_mul_f32 v[74:75], v[74:75], v[76:77]
	v_cvt_pk_bf16_f32 v68, v68, v69
	v_cvt_pk_bf16_f32 v69, v70, v71
	v_cvt_pk_bf16_f32 v70, v72, v73
	v_cvt_pk_bf16_f32 v71, v74, v75
	ds_write_b128 v163, v[68:71]
	s_cmpk_eq_i32 s97, 0x1000
	s_cbranch_scc1 .Lml_ld_a
	global_load_dwordx4 v[0:3], v[4:5], off
.Lml_ld_a:
	v_lshl_add_u32 v72, v164, 2, s82
	ds_read_b128 v[68:71], v72 offset:1024
	ds_read_b128 v[72:75], v72 offset:1040
	ds_read_u16 v76, v165 offset:33792
	ds_read_u16 v77, v165 offset:34320
	ds_read_u16 v78, v166 offset:35904
	ds_read_u16 v79, v166 offset:36432
	ds_read_u16 v80, v165 offset:34848
	ds_read_u16 v81, v166 offset:36960
	ds_read_u16 v82, v166 offset:37488
	ds_read_u16 v83, v165 offset:35376
	s_waitcnt lgkmcnt(6)
	v_lshlrev_b32_e32 v77, 16, v77
	v_lshlrev_b32_e32 v76, 16, v76
	v_pk_mul_f32 v[68:69], v[68:69], v[76:77]
	s_waitcnt lgkmcnt(4)
	v_lshlrev_b32_e32 v77, 16, v79
	v_lshlrev_b32_e32 v76, 16, v78
	v_pk_mul_f32 v[72:73], v[72:73], v[76:77]
	s_waitcnt lgkmcnt(0)
	v_lshlrev_b32_e32 v77, 16, v83
	v_lshlrev_b32_e32 v76, 16, v80
	v_pk_mul_f32 v[70:71], v[70:71], v[76:77]
	v_lshlrev_b32_e32 v77, 16, v82
	v_lshlrev_b32_e32 v76, 16, v81
	v_pk_mul_f32 v[74:75], v[74:75], v[76:77]
	v_cvt_pk_bf16_f32 v68, v68, v69
	v_cvt_pk_bf16_f32 v69, v70, v71
	v_cvt_pk_bf16_f32 v70, v72, v73
	v_cvt_pk_bf16_f32 v71, v74, v75
	ds_write_b128 v167, v[68:71]
	s_cmpk_eq_i32 s97, 0x1000
	s_cbranch_scc1 .Lml_ld_b
	global_load_dwordx4 v[4:7], v[4:5], off offset:2048
.Lml_ld_b:
	v_lshl_add_u32 v72, v168, 2, s82
	ds_read_b128 v[68:71], v72 offset:1024
	ds_read_b128 v[72:75], v72 offset:1040
	ds_read_u16 v76, v169 offset:33792
	ds_read_u16 v77, v169 offset:34320
	ds_read_u16 v78, v170 offset:35904
	ds_read_u16 v79, v170 offset:36432
	ds_read_u16 v80, v169 offset:34848
	ds_read_u16 v81, v170 offset:36960
	ds_read_u16 v82, v170 offset:37488
	ds_read_u16 v83, v169 offset:35376
	s_waitcnt lgkmcnt(6)
	v_lshlrev_b32_e32 v77, 16, v77
	v_lshlrev_b32_e32 v76, 16, v76
	v_pk_mul_f32 v[68:69], v[68:69], v[76:77]
	s_waitcnt lgkmcnt(4)
	v_lshlrev_b32_e32 v77, 16, v79
	v_lshlrev_b32_e32 v76, 16, v78
	v_pk_mul_f32 v[72:73], v[72:73], v[76:77]
	s_waitcnt lgkmcnt(0)
	v_lshlrev_b32_e32 v77, 16, v83
	v_lshlrev_b32_e32 v76, 16, v80
	v_pk_mul_f32 v[70:71], v[70:71], v[76:77]
	v_lshlrev_b32_e32 v77, 16, v82
	v_lshlrev_b32_e32 v76, 16, v81
	v_pk_mul_f32 v[74:75], v[74:75], v[76:77]
	v_cvt_pk_bf16_f32 v68, v68, v69
	v_cvt_pk_bf16_f32 v69, v70, v71
	v_cvt_pk_bf16_f32 v70, v72, v73
	v_cvt_pk_bf16_f32 v71, v74, v75
	ds_write_b128 v171, v[68:71]
	s_cmpk_eq_i32 s97, 0x1000
	s_cbranch_scc1 .Lml_ld_c
	global_load_dwordx4 v[8:11], v[12:13], off
; DI unsigned pk2(float a, float b) { f32x2 v = {a, b}; hbf2 r = __builtin_convertvector(v, hbf2); return __builtin_bit_cast(unsigned, r); }
; DI void mlstm_unit(const Params& p, unsigned char* smem, int unit) {
;     ...
; #pragma unroll
;         for (int i = 0; i < 4; ++i) {
;             const int task = tid + 512 * i, k = task & 255, s0 = (task >> 8) * 8;
;             float v[8];
;             const f32x4 wa = *(const f32x4*)(sws + s0), wb = *(const f32x4*)(sws + s0 + 4);
; #pragma unroll
;             for (int e = 0; e < 4; ++e) { v[e] = bf2f(sK[(s0 + e) * 264 + k]) * wa[e]; v[4 + e] = bf2f(sK[(s0 + 4 + e) * 264 + k]) * wb[e]; }
;             u32x4 w; w.x = pk2(v[0], v[1]); w.y = pk2(v[2], v[3]); w.z = pk2(v[4], v[5]); w.w = pk2(v[6], v[7]);
;             *(u32x4*)(sKwt + k * 72 + s0) = w;
;         }
;         f32x4 accH[2];
;         {
;             bf16x8 Bq[8];
; #pragma unroll
;             for (int ks = 0; ks < 8; ++ks) Bq[ks] = *(const bf16x8*)(sQ + (ti * 16 + fr) * 264 + ks * 32 + fq * 8);
;             const int t = ti * 16 + fr;
;             const float Mt_t = sMt[t];
; #pragma unroll
;             for (int x = 0; x < 2; ++x) {
;                 const int si = pi + x;
;                 if (si > ti) {
;                     if (fq == 0) srs[si * 64 + t] = 0.f;
;                     *(u32x2*)(sSd + t * 72 + si * 16 + fq * 4) = (u32x2){0u, 0u};
;                     continue;
;                 }
;                 f32x4 aS = (f32x4){0.f, 0.f, 0.f, 0.f};
; #pragma unroll
;                 for (int ks = 0; ks < 8; ++ks) aS = mfma16(*(const bf16x8*)(sK + (si * 16 + fr) * 264 + ks * 32 + fq * 8), Bq[ks], aS);
;                 float val[4]; float ps = 0.f;
;                 const f32x4 gv = *(const f32x4*)(sg + si * 16 + fq * 4);
; #pragma unroll
;                 for (int j = 0; j < 4; ++j) {
;                     const int s = si * 16 + fq * 4 + j;
;                     const float e = __expf(fminf(gv[j] - Mt_t, 0.f));
;                     const float d = (s <= t) ? e : 0.f;
;                     val[j] = aS[j] * d; ps += val[j];
;                 }
;                 ps = sum_x16_x32(ps);
;                 if (fq == 0) srs[si * 64 + t] = ps;
;                 u32x2 w; w.x = pk2(val[0], val[1]); w.y = pk2(val[2], val[3]);
;                 *(u32x2*)(sSd + t * 72 + si * 16 + fq * 4) = w;
;             }
.Lml_ld_c:
	v_lshl_add_u32 v72, v172, 2, s82
	ds_read_b128 v[68:71], v72 offset:1024
	ds_read_b128 v[72:75], v72 offset:1040
	ds_read_u16 v76, v173 offset:33792
	ds_read_u16 v77, v173 offset:34320
	ds_read_u16 v78, v174 offset:35904
	ds_read_u16 v79, v174 offset:36432
	ds_read_u16 v80, v173 offset:34848
	ds_read_u16 v81, v174 offset:36960
	ds_read_u16 v82, v174 offset:37488
	ds_read_u16 v83, v173 offset:35376
	s_waitcnt lgkmcnt(6)
	v_lshlrev_b32_e32 v77, 16, v77
	v_lshlrev_b32_e32 v76, 16, v76
	v_pk_mul_f32 v[68:69], v[68:69], v[76:77]
	s_waitcnt lgkmcnt(4)
	v_lshlrev_b32_e32 v77, 16, v79
	v_lshlrev_b32_e32 v76, 16, v78
	v_pk_mul_f32 v[72:73], v[72:73], v[76:77]
	s_waitcnt lgkmcnt(0)
	v_lshlrev_b32_e32 v77, 16, v83
	v_lshlrev_b32_e32 v76, 16, v80
	v_pk_mul_f32 v[70:71], v[70:71], v[76:77]
	v_lshlrev_b32_e32 v77, 16, v82
	v_lshlrev_b32_e32 v76, 16, v81
	v_pk_mul_f32 v[74:75], v[74:75], v[76:77]
	v_cvt_pk_bf16_f32 v68, v68, v69
	v_cvt_pk_bf16_f32 v69, v70, v71
	v_cvt_pk_bf16_f32 v70, v72, v73
	v_cvt_pk_bf16_f32 v71, v74, v75
	ds_write_b128 v176, v[68:71]
	s_cmpk_eq_i32 s97, 0x1000
	s_cbranch_scc1 .Lml_ld_d
	global_load_dwordx4 v[12:15], v[12:13], off offset:2048
.Lml_ld_d:
	ds_read_b128 v[92:95], v190 offset:64
	ds_read_b128 v[88:91], v190 offset:128
	ds_read_b128 v[84:87], v190 offset:192
	ds_read_b128 v[80:83], v190 offset:256
	ds_read_b128 v[76:79], v190 offset:320
	ds_read_b128 v[72:75], v190 offset:384
	ds_read_b128 v[68:71], v190 offset:448
	v_lshl_add_u32 v200, v144, 2, s82
	ds_read_b128 v[96:99], v190
	ds_read_b32 v201, v200 offset:256
	v_lshl_add_u32 v202, v147, 2, s82
	s_and_saveexec_b64 s[72:73], s[14:15]
	s_xor_b64 vcc, exec, s[72:73]
	s_cbranch_execz .LBB0_389
	v_add_u32_e32 v203, v149, v177
	ds_read_b128 v[208:211], v203 offset:33792
	ds_read_b128 v[212:215], v203 offset:33856
	ds_read_b128 v[216:219], v203 offset:33920
	ds_read_b128 v[220:223], v203 offset:33984
	ds_read_b128 v[224:227], v203 offset:34048
	s_waitcnt lgkmcnt(4)
	v_mfma_f32_16x16x32_bf16 v[100:103], v[208:211], v[96:99], 0
	ds_read_b128 v[208:211], v203 offset:34112
	s_waitcnt lgkmcnt(4)
	v_mfma_f32_16x16x32_bf16 v[100:103], v[212:215], v[92:95], v[100:103]
	ds_read_b128 v[212:215], v203 offset:34176
	s_waitcnt lgkmcnt(4)
	v_mfma_f32_16x16x32_bf16 v[100:103], v[216:219], v[88:91], v[100:103]
	ds_read_b128 v[216:219], v203 offset:34240
	v_lshl_add_u32 v203, v146, 2, v202
	s_waitcnt lgkmcnt(4)
	v_mfma_f32_16x16x32_bf16 v[100:103], v[220:223], v[84:87], v[100:103]
	s_waitcnt lgkmcnt(3)
	v_mfma_f32_16x16x32_bf16 v[100:103], v[224:227], v[80:83], v[100:103]
	s_waitcnt lgkmcnt(2)
	v_mfma_f32_16x16x32_bf16 v[100:103], v[208:211], v[76:79], v[100:103]
	ds_read_b128 v[208:211], v203
	s_waitcnt lgkmcnt(2)
	v_mfma_f32_16x16x32_bf16 v[100:103], v[212:215], v[72:75], v[100:103]
	s_waitcnt lgkmcnt(1)
	v_mfma_f32_16x16x32_bf16 v[100:103], v[216:219], v[68:71], v[100:103]
	s_waitcnt lgkmcnt(0)
	v_sub_f32_e32 v203, v208, v201
	v_sub_f32_e32 v204, v209, v201
	v_min_f32_e32 v203, 0, v203
	v_min_f32_e32 v204, 0, v204
	v_mul_f32_e32 v203, 0x3fb8aa3b, v203
	v_mul_f32_e32 v204, 0x3fb8aa3b, v204
	v_exp_f32_e32 v203, v203
	v_exp_f32_e32 v204, v204
	s_nop 0
	v_cndmask_b32_e64 v205, 0, v204, s[18:19]
	v_cndmask_b32_e64 v204, v203, 0, s[16:17]
	v_pk_mul_f32 v[100:101], v[100:101], v[204:205]
	v_sub_f32_e32 v204, v210, v201
	v_sub_f32_e32 v205, v211, v201
	v_min_f32_e32 v204, 0, v204
	v_min_f32_e32 v205, 0, v205
	v_mul_f32_e32 v204, 0x3fb8aa3b, v204
	v_mul_f32_e32 v205, 0x3fb8aa3b, v205
	v_exp_f32_e32 v204, v204
	v_exp_f32_e32 v205, v205
	v_add_f32_e32 v203, 0, v100
	v_add_f32_e32 v203, v101, v203
	v_cndmask_b32_e64 v204, v204, 0, s[22:23]
	v_cndmask_b32_e64 v205, v205, 0, s[20:21]
	v_pk_mul_f32 v[102:103], v[102:103], v[204:205]
	s_nop 0
	v_add_f32_e32 v203, v102, v203
	v_add_f32_e32 v203, v103, v203
	v_mov_b32_e32 v204, v203
	s_nop 1
	v_permlane16_swap_b32_e32 v203, v204
	v_add_f32_e32 v203, v203, v204
	v_mov_b32_e32 v204, v203
	s_nop 1
	v_permlane32_swap_b32_e32 v203, v204
	s_and_saveexec_b64 s[72:73], s[8:9]
	v_add_f32_e32 v203, v203, v204
	v_add_u32_e32 v204, v148, v179
	ds_write_b32 v204, v203
	s_or_b64 exec, exec, s[72:73]
	v_cvt_pk_bf16_f32 v100, v100, v101
	v_cvt_pk_bf16_f32 v101, v102, v103
	ds_write_b64 v180, v[100:101]
	s_andn2_saveexec_b64 s[72:73], vcc
	s_cbranch_execnz .LBB0_390

; DI float bflo(unsigned u) { return __uint_as_float(u << 16); }
; DI float bfhi(unsigned u) { return __uint_as_float(u & 0xffff0000u); }
; DI f32x4 mfma16(bf16x8 a, bf16x8 b, f32x4 c) { return __builtin_amdgcn_mfma_f32_16x16x32_bf16(a, b, c, 0, 0, 0); }
; DI void mlstm_unit(const Params& p, unsigned char* smem, int unit) {
;     ...
;         for (int i = 0; i < 4; ++i) {
;             const int vid = tid + 512 * i, s = vid >> 5, kv = vid & 31;
;             const size_t row = (size_t)(base + (s < nv ? s : nv - 1));
;             rq[i] = *(const u32x4*)(T1 + row * 4096 + h * 256 + kv * 8);
;             rk[i] = *(const u32x4*)(T1 + row * 4096 + 1024 + h * 256 + kv * 8);
;         }
;         {
;             const int s = lane, vv = wid;
;             const size_t row = (size_t)(base + (s < nv ? s : nv - 1));
;             rv = *(const u32x4*)(T1 + row * 4096 + 2048 + h * 256 + sl * 64 + vv * 8);
;         }
;     ...
; #pragma unroll
;             for (int x = 0; x < 2; ++x) {
;                 const int vi = pi + x;
;                 f32x4 aH = (f32x4){0.f, 0.f, 0.f, 0.f};
; #pragma unroll
;                 for (int ks = 0; ks < 8; ++ks) aH = mfma16(*(const bf16x8*)(sCb + (vi * 16 + fr) * 264 + ks * 32 + fq * 8), Bq[ks], aH);
;                 accH[x] = aH;
;             }
;         }
;         {
;             const int t = tid >> 3, part = tid & 7;
;             float s = 0.f;
; #pragma unroll
;             for (int i = 0; i < 4; ++i) {
;                 const u32x4 qv = *(const u32x4*)(sQ + t * 264 + part * 32 + i * 8);
;                 const f32x4 na = *(const f32x4*)(sN + part * 32 + i * 8), nb = *(const f32x4*)(sN + part * 32 + i * 8 + 4);
;                 s += bflo(qv.x) * na[0] + bfhi(qv.x) * na[1] + bflo(qv.y) * na[2] + bfhi(qv.y) * na[3]
;                    + bflo(qv.z) * nb[0] + bfhi(qv.z) * nb[1] + bflo(qv.w) * nb[2] + bfhi(qv.w) * nb[3];
;             }
;             s += __shfl_xor(s, 1); s += __shfl_xor(s, 2); s += __shfl_xor(s, 4);
;             if (part == 0) snq[t] = s;
;         }
.LBB0_397:
	s_or_b64 exec, exec, vcc
	s_cmpk_eq_i32 s97, 0x1000
	s_cbranch_scc1 .Lml_ld_e
	global_load_dwordx4 v[16:19], v[20:21], off
	s_nop 0
	global_load_dwordx4 v[20:23], v[20:21], off offset:2048
.Lml_ld_e:
	ds_read_b128 v[202:205], v193
	ds_read_b128 v[208:211], v193 offset:64
	ds_read_b128 v[212:215], v193 offset:128
	ds_read_b128 v[216:219], v193 offset:192
	ds_read_b128 v[220:223], v193 offset:256
	ds_read_b128 v[224:227], v193 offset:320
	s_waitcnt lgkmcnt(5)
	v_mfma_f32_16x16x32_bf16 v[100:103], v[202:205], v[96:99], 0
	ds_read_b128 v[202:205], v193 offset:384
	s_waitcnt lgkmcnt(5)
	v_mfma_f32_16x16x32_bf16 v[100:103], v[208:211], v[92:95], v[100:103]
	ds_read_b128 v[208:211], v193 offset:448
	s_waitcnt lgkmcnt(5)
	v_mfma_f32_16x16x32_bf16 v[100:103], v[212:215], v[88:91], v[100:103]
	ds_read_b128 v[212:215], v193 offset:8448
	s_waitcnt lgkmcnt(5)
	v_mfma_f32_16x16x32_bf16 v[100:103], v[216:219], v[84:87], v[100:103]
	ds_read_b128 v[216:219], v193 offset:8512
	s_waitcnt lgkmcnt(5)
	v_mfma_f32_16x16x32_bf16 v[100:103], v[220:223], v[80:83], v[100:103]
	ds_read_b128 v[220:223], v193 offset:8576
	s_waitcnt lgkmcnt(5)
	v_mfma_f32_16x16x32_bf16 v[100:103], v[224:227], v[76:79], v[100:103]
	s_waitcnt lgkmcnt(4)
	v_mfma_f32_16x16x32_bf16 v[100:103], v[202:205], v[72:75], v[100:103]
	ds_read_b128 v[202:205], v193 offset:8640
	s_waitcnt lgkmcnt(4)
	v_mfma_f32_16x16x32_bf16 v[100:103], v[208:211], v[68:71], v[100:103]
	ds_read_b128 v[208:211], v193 offset:8704
	s_cmpk_eq_i32 s97, 0x1000
	s_cbranch_scc1 .Lml_ld_f
	global_load_dwordx4 v[24:27], v[28:29], off
	s_nop 0
	global_load_dwordx4 v[28:31], v[28:29], off offset:2048
.Lml_ld_f:
	s_waitcnt lgkmcnt(4)
	v_mfma_f32_16x16x32_bf16 v[224:227], v[212:215], v[96:99], 0
	ds_read_b128 v[212:215], v193 offset:8768
	s_waitcnt lgkmcnt(4)
	v_mfma_f32_16x16x32_bf16 v[224:227], v[216:219], v[92:95], v[224:227]
	ds_read_b128 v[216:219], v193 offset:8832
	s_waitcnt lgkmcnt(4)
	v_mfma_f32_16x16x32_bf16 v[224:227], v[220:223], v[88:91], v[224:227]
	ds_read_b128 v[220:223], v193 offset:8896
	s_waitcnt lgkmcnt(4)
	v_mfma_f32_16x16x32_bf16 v[224:227], v[202:205], v[84:87], v[224:227]
	s_waitcnt lgkmcnt(3)
	v_mfma_f32_16x16x32_bf16 v[224:227], v[208:211], v[80:83], v[224:227]
	s_waitcnt lgkmcnt(2)
	v_mfma_f32_16x16x32_bf16 v[224:227], v[212:215], v[76:79], v[224:227]
	s_waitcnt lgkmcnt(1)
	v_mfma_f32_16x16x32_bf16 v[224:227], v[216:219], v[72:75], v[224:227]
	s_waitcnt lgkmcnt(0)
	v_mfma_f32_16x16x32_bf16 v[68:71], v[220:223], v[68:71], v[224:227]
	s_cmpk_eq_i32 s97, 0x1000
	s_cbranch_scc1 .Lml_ld_g
	global_load_dwordx4 v[32:35], v[32:33], off
.Lml_ld_g:
	s_nop 2
	ds_read_b128 v[72:75], v151
	ds_read_b128 v[76:79], v151 offset:16
	ds_read_b128 v[80:83], v151 offset:32
	ds_read_b128 v[84:87], v151 offset:48
	ds_read_b128 v[88:91], v152
	ds_read_b128 v[92:95], v152 offset:16
	ds_read_b128 v[96:99], v152 offset:32
	ds_read_b128 v[202:205], v152 offset:48
	s_waitcnt lgkmcnt(7)
	v_lshlrev_b32_e32 v201, 16, v72
	v_and_b32_e32 v72, 0xffff0000, v72
	s_waitcnt lgkmcnt(3)
	v_mul_f32_e32 v72, v89, v72
	v_fmac_f32_e32 v72, v88, v201
	v_lshlrev_b32_e32 v88, 16, v73
	v_fmac_f32_e32 v72, v90, v88
	v_and_b32_e32 v73, 0xffff0000, v73
	v_fmac_f32_e32 v72, v91, v73
	v_lshlrev_b32_e32 v73, 16, v74
	s_waitcnt lgkmcnt(2)
	v_fmac_f32_e32 v72, v92, v73
	v_and_b32_e32 v73, 0xffff0000, v74
	v_fmac_f32_e32 v72, v93, v73
	v_lshlrev_b32_e32 v73, 16, v75
	v_fmac_f32_e32 v72, v94, v73
	v_and_b32_e32 v73, 0xffff0000, v75
	v_and_b32_e32 v74, 0xffff0000, v76
	v_fmac_f32_e32 v72, v95, v73
	v_lshlrev_b32_e32 v73, 16, v76
	s_waitcnt lgkmcnt(1)
	v_mul_f32_e32 v74, v97, v74
	v_fmac_f32_e32 v74, v96, v73
	v_lshlrev_b32_e32 v73, 16, v77
	v_fmac_f32_e32 v74, v98, v73
	v_and_b32_e32 v73, 0xffff0000, v77
	v_fmac_f32_e32 v74, v99, v73
	v_lshlrev_b32_e32 v73, 16, v78
	s_waitcnt lgkmcnt(0)
	v_fmac_f32_e32 v74, v202, v73
	v_and_b32_e32 v73, 0xffff0000, v78
	v_fmac_f32_e32 v74, v203, v73
	v_lshlrev_b32_e32 v73, 16, v79
	v_fmac_f32_e32 v74, v204, v73
	v_and_b32_e32 v73, 0xffff0000, v79
	v_add_f32_e32 v72, 0, v72
	v_fmac_f32_e32 v74, v205, v73
	v_add_f32_e32 v88, v72, v74
	ds_read_b128 v[72:75], v152 offset:64
	ds_read_b128 v[76:79], v152 offset:80
	v_lshlrev_b32_e32 v89, 16, v80
	v_and_b32_e32 v80, 0xffff0000, v80
	s_waitcnt lgkmcnt(1)
	v_mul_f32_e32 v73, v73, v80
	v_fmac_f32_e32 v73, v72, v89
	v_lshlrev_b32_e32 v72, 16, v81
	v_fmac_f32_e32 v73, v74, v72
	v_and_b32_e32 v72, 0xffff0000, v81
	v_fmac_f32_e32 v73, v75, v72
	v_lshlrev_b32_e32 v72, 16, v82
	s_waitcnt lgkmcnt(0)
	v_fmac_f32_e32 v73, v76, v72
	v_and_b32_e32 v72, 0xffff0000, v82
	v_fmac_f32_e32 v73, v77, v72
	v_lshlrev_b32_e32 v72, 16, v83
	v_fmac_f32_e32 v73, v78, v72
	v_and_b32_e32 v72, 0xffff0000, v83
	v_fmac_f32_e32 v73, v79, v72
	v_add_f32_e32 v80, v88, v73
	ds_read_b128 v[72:75], v152 offset:96
	ds_read_b128 v[76:79], v152 offset:112
	v_and_b32_e32 v82, 0xffff0000, v84
	v_lshlrev_b32_e32 v81, 16, v84
	s_waitcnt lgkmcnt(1)
	v_mul_f32_e32 v73, v73, v82
	v_fmac_f32_e32 v73, v72, v81
	v_lshlrev_b32_e32 v72, 16, v85
	v_fmac_f32_e32 v73, v74, v72
	v_and_b32_e32 v72, 0xffff0000, v85
	v_fmac_f32_e32 v73, v75, v72
	v_lshlrev_b32_e32 v72, 16, v86
	s_waitcnt lgkmcnt(0)
	v_fmac_f32_e32 v73, v76, v72
	v_and_b32_e32 v72, 0xffff0000, v86
	v_fmac_f32_e32 v73, v77, v72
	v_lshlrev_b32_e32 v72, 16, v87
	v_fmac_f32_e32 v73, v78, v72
	v_and_b32_e32 v72, 0xffff0000, v87
	v_fmac_f32_e32 v73, v79, v72
	v_add_f32_e32 v72, v80, v73
	ds_bpermute_b32 v73, v153, v72
	s_waitcnt lgkmcnt(0)
	v_add_f32_e32 v72, v72, v73
	ds_bpermute_b32 v73, v154, v72
	s_waitcnt lgkmcnt(0)
	v_add_f32_e32 v72, v72, v73
	ds_bpermute_b32 v73, v155, v72
	s_and_saveexec_b64 s[72:73], s[10:11]
	s_cbranch_execz .LBB0_399
	s_waitcnt lgkmcnt(0)
	v_add_f32_e32 v72, v72, v73
	ds_write_b32 v157, v72

; DI unsigned pk2(float a, float b) { f32x2 v = {a, b}; hbf2 r = __builtin_convertvector(v, hbf2); return __builtin_bit_cast(unsigned, r); }
; DI int tid_fresh() { int t = threadIdx.x; asm volatile("" : "+v"(t)); return t; }
; DI float sum_x16_x32(float x) { return sum_x32(sum_x16(x)); }
; DI f32x4 mfma16(bf16x8 a, bf16x8 b, f32x4 c) { return __builtin_amdgcn_mfma_f32_16x16x32_bf16(a, b, c, 0, 0, 0); }
; template <class Epi> DI void small_gemm(const bf16_t* A, const bf16_t* Bt, int N, int K, const Epi& E) {
;     const int tid = tid_fresh(), lane = tid & 63, wid = tid >> 6, fr = lane & 15, fq = lane >> 4;
;     const int nw = gridDim.x * 8;
;     for (int tile = blockIdx.x * 8 + wid; tile < (N >> 4); tile += nw) {
;         const int n0 = tile * 16;
;         f32x4 acc = (f32x4){0.f, 0.f, 0.f, 0.f};
;         const bf16_t* ap = A + (size_t)fr * K + fq * 8;
;         const bf16_t* bp = Bt + (size_t)(n0 + fr) * K + fq * 8;
; #pragma unroll 16
;         for (int k = 0; k < K; k += 32) acc = mfma16(*(const bf16x8*)(bp + k), *(const bf16x8*)(ap + k), acc);
;         E(acc, fr, n0 + fq * 4, fq);
;     }
; }
;     DI void operator()(f32x4 acc, int row, int n, int fq) const {
;         const size_t r = (size_t)(MR + row);
;         const f32x4 rv = MODE == 0 ? *(const f32x4*)(meta + (size_t)row * 1024 + n) : *(const f32x4*)(h + r * 1024 + n);
;         const f32x4 v = acc + rv;
;         *(f32x4*)(h + r * 1024 + n) = v;
;         u32x2 w; w.x = pk2(v[0], v[1]); w.y = pk2(v[2], v[3]);
;         *(u32x2*)(hb + r * 1024 + n) = w;
;         float sq = v[0] * v[0] + v[1] * v[1] + v[2] * v[2] + v[3] * v[3];
;         sq = sum_x16_x32(sq);
;         if (fq == 0) atomicAdd(ss + r, sq);
;     }
.LBB0_749:
	v_lshl_add_u64 v[24:25], v[18:19], 0, v[4:5]
	v_add_co_u32_e32 v92, vcc, 0xc00000, v24
	v_lshl_add_u64 v[26:27], v[20:21], 0, v[4:5]
	s_nop 0
	v_addc_co_u32_e32 v93, vcc, 0, v25, vcc
	v_add_co_u32_e32 v94, vcc, 0x1fd47000, v26
	s_addk_i32 s3, 0x200
	s_nop 0
	v_addc_co_u32_e32 v95, vcc, 0, v27, vcc
	global_load_dwordx4 v[24:27], v[92:93], off
	global_load_dwordx4 v[100:103], v[94:95], off offset:2816
	global_load_dwordx4 v[28:31], v[92:93], off offset:64
	global_load_dwordx4 v[104:107], v[94:95], off offset:2880
	global_load_dwordx4 v[32:35], v[92:93], off offset:128
	global_load_dwordx4 v[108:111], v[94:95], off offset:2944
	global_load_dwordx4 v[36:39], v[92:93], off offset:192
	global_load_dwordx4 v[112:115], v[94:95], off offset:3008
	global_load_dwordx4 v[40:43], v[92:93], off offset:256
	global_load_dwordx4 v[116:119], v[94:95], off offset:3072
	global_load_dwordx4 v[44:47], v[92:93], off offset:320
	global_load_dwordx4 v[120:123], v[94:95], off offset:3136
	global_load_dwordx4 v[48:51], v[92:93], off offset:384
	global_load_dwordx4 v[124:127], v[94:95], off offset:3200
	global_load_dwordx4 v[52:55], v[92:93], off offset:448
	global_load_dwordx4 v[128:131], v[94:95], off offset:3264
	global_load_dwordx4 v[56:59], v[92:93], off offset:512
	global_load_dwordx4 v[132:135], v[94:95], off offset:3328
	global_load_dwordx4 v[60:63], v[92:93], off offset:576
	global_load_dwordx4 v[136:139], v[94:95], off offset:3392
	global_load_dwordx4 v[64:67], v[92:93], off offset:640
	global_load_dwordx4 v[140:143], v[94:95], off offset:3456
	global_load_dwordx4 v[68:71], v[92:93], off offset:704
	global_load_dwordx4 v[144:147], v[94:95], off offset:3520
	global_load_dwordx4 v[72:75], v[92:93], off offset:768
	global_load_dwordx4 v[148:151], v[94:95], off offset:3584
	global_load_dwordx4 v[76:79], v[92:93], off offset:832
	global_load_dwordx4 v[152:155], v[94:95], off offset:3648
	global_load_dwordx4 v[80:83], v[92:93], off offset:896
	global_load_dwordx4 v[156:159], v[94:95], off offset:3712
	global_load_dwordx4 v[164:167], v[92:93], off offset:960
	global_load_dwordx4 v[160:163], v[94:95], off offset:3776
	v_lshl_add_u64 v[18:19], v[18:19], 0, s[8:9]
	s_cmpk_gt_u32 s3, 0x7df
	v_lshl_add_u64 v[20:21], v[20:21], 0, s[8:9]
	s_waitcnt vmcnt(30)
	v_mfma_f32_16x16x32_bf16 v[0:3], v[24:27], v[100:103], v[0:3]
	s_waitcnt vmcnt(28)
	v_mfma_f32_16x16x32_bf16 v[0:3], v[28:31], v[104:107], v[0:3]
	s_waitcnt vmcnt(26)
	v_mfma_f32_16x16x32_bf16 v[0:3], v[32:35], v[108:111], v[0:3]
	s_waitcnt vmcnt(24)
	v_mfma_f32_16x16x32_bf16 v[0:3], v[36:39], v[112:115], v[0:3]
	s_waitcnt vmcnt(22)
	v_mfma_f32_16x16x32_bf16 v[0:3], v[40:43], v[116:119], v[0:3]
	s_waitcnt vmcnt(20)
	v_mfma_f32_16x16x32_bf16 v[0:3], v[44:47], v[120:123], v[0:3]
	s_waitcnt vmcnt(18)
	v_mfma_f32_16x16x32_bf16 v[0:3], v[48:51], v[124:127], v[0:3]
	s_waitcnt vmcnt(16)
	v_mfma_f32_16x16x32_bf16 v[0:3], v[52:55], v[128:131], v[0:3]
	s_waitcnt vmcnt(14)
	v_mfma_f32_16x16x32_bf16 v[0:3], v[56:59], v[132:135], v[0:3]
	s_waitcnt vmcnt(12)
	v_mfma_f32_16x16x32_bf16 v[0:3], v[60:63], v[136:139], v[0:3]
	s_waitcnt vmcnt(10)
	v_mfma_f32_16x16x32_bf16 v[0:3], v[64:67], v[140:143], v[0:3]
	s_waitcnt vmcnt(8)
	v_mfma_f32_16x16x32_bf16 v[0:3], v[68:71], v[144:147], v[0:3]
	s_waitcnt vmcnt(6)
	v_mfma_f32_16x16x32_bf16 v[0:3], v[72:75], v[148:151], v[0:3]
	s_waitcnt vmcnt(4)
	v_mfma_f32_16x16x32_bf16 v[0:3], v[76:79], v[152:155], v[0:3]
	s_waitcnt vmcnt(2)
	v_mfma_f32_16x16x32_bf16 v[0:3], v[80:83], v[156:159], v[0:3]
	s_waitcnt vmcnt(0)
	v_mfma_f32_16x16x32_bf16 v[0:3], v[164:167], v[160:163], v[0:3]
	s_cbranch_scc0 .LBB0_749
	v_lshl_or_b32 v24, v22, 4, v23
	v_ashrrev_i32_e32 v25, 31, v24
	v_lshlrev_b64 v[26:27], 2, v[24:25]
	v_lshl_add_u64 v[18:19], v[6:7], 0, v[26:27]
	global_load_dwordx4 v[18:21], v[18:19], off
	v_lshl_add_u64 v[26:27], v[8:9], 0, v[26:27]
	v_lshl_add_u64 v[24:25], v[24:25], 1, v[10:11]
	s_waitcnt vmcnt(0)
	v_pk_add_f32 v[2:3], v[2:3], v[20:21]
	v_pk_add_f32 v[0:1], v[0:1], v[18:19]
	global_store_dwordx4 v[26:27], v[0:3], off
	v_cvt_pk_bf16_f32 v18, v0, v1
	v_cvt_pk_bf16_f32 v19, v2, v3
	v_mul_f32_e32 v1, v1, v1
	v_fmac_f32_e32 v1, v0, v0
	v_fmac_f32_e32 v1, v2, v2
	v_fmac_f32_e32 v1, v3, v3
	v_mov_b32_e32 v0, v1
	s_nop 1
	v_permlane16_swap_b32_e32 v1, v0
	v_add_f32_e32 v0, v1, v0
	v_mov_b32_e32 v1, v0
	s_nop 1
	v_permlane32_swap_b32_e32 v0, v1
	global_store_dwordx2 v[24:25], v[18:19], off
	s_and_saveexec_b64 s[10:11], s[0:1]
	s_cbranch_execz .LBB0_747
	v_add_f32_e32 v0, v0, v1
	global_atomic_add_f32 v[12:13], v0, off
	s_branch .LBB0_747

; DI unsigned pk2(float a, float b) { f32x2 v = {a, b}; hbf2 r = __builtin_convertvector(v, hbf2); return __builtin_bit_cast(unsigned, r); }
; DI int tid_fresh() { int t = threadIdx.x; asm volatile("" : "+v"(t)); return t; }
; DI f32x4 mfma16(bf16x8 a, bf16x8 b, f32x4 c) { return __builtin_amdgcn_mfma_f32_16x16x32_bf16(a, b, c, 0, 0, 0); }
; template <class Epi> DI void small_gemm(const bf16_t* A, const bf16_t* Bt, int N, int K, const Epi& E) {
;     const int tid = tid_fresh(), lane = tid & 63, wid = tid >> 6, fr = lane & 15, fq = lane >> 4;
;     const int nw = gridDim.x * 8;
;     for (int tile = blockIdx.x * 8 + wid; tile < (N >> 4); tile += nw) {
;         const int n0 = tile * 16;
;         f32x4 acc = (f32x4){0.f, 0.f, 0.f, 0.f};
;         const bf16_t* ap = A + (size_t)fr * K + fq * 8;
;         const bf16_t* bp = Bt + (size_t)(n0 + fr) * K + fq * 8;
; #pragma unroll 16
;         for (int k = 0; k < K; k += 32) acc = mfma16(*(const bf16x8*)(bp + k), *(const bf16x8*)(ap + k), acc);
;         E(acc, fr, n0 + fq * 4, fq);
;     }
; }
;     DI void operator()(f32x4 v, int row, int n, int fq) const {
;         const size_t r = (size_t)(MR + row);
;         const float rstd = rsqrtf(ss[r] * (1.0f / 1024.0f) + EPS);
; #pragma unroll
;         for (int j = 0; j < 4; ++j) { const float a = fmaxf(v[j] * rstd, 0.f); v[j] = a * a; }
;         u32x2 w; w.x = pk2(v[0], v[1]); w.y = pk2(v[2], v[3]);
;         *(u32x2*)(HID + r * 4096 + n) = w;
;     }
.LBB0_909:
	v_lshl_add_u64 v[22:23], v[14:15], 0, v[4:5]
	v_add_co_u32_e32 v90, vcc, 0x1000000, v22
	v_lshl_add_u64 v[24:25], v[16:17], 0, v[4:5]
	s_nop 0
	v_addc_co_u32_e32 v91, vcc, 0, v23, vcc
	v_add_co_u32_e32 v92, vcc, 0x7ac7000, v24
	s_addk_i32 s0, 0x200
	s_nop 0
	v_addc_co_u32_e32 v93, vcc, 0, v25, vcc
	global_load_dwordx4 v[22:25], v[90:91], off
	global_load_dwordx4 v[100:103], v[92:93], off offset:2816
	global_load_dwordx4 v[26:29], v[90:91], off offset:64
	global_load_dwordx4 v[104:107], v[92:93], off offset:2880
	global_load_dwordx4 v[30:33], v[90:91], off offset:128
	global_load_dwordx4 v[108:111], v[92:93], off offset:2944
	global_load_dwordx4 v[34:37], v[90:91], off offset:192
	global_load_dwordx4 v[112:115], v[92:93], off offset:3008
	global_load_dwordx4 v[38:41], v[90:91], off offset:256
	global_load_dwordx4 v[116:119], v[92:93], off offset:3072
	global_load_dwordx4 v[42:45], v[90:91], off offset:320
	global_load_dwordx4 v[120:123], v[92:93], off offset:3136
	global_load_dwordx4 v[46:49], v[90:91], off offset:384
	global_load_dwordx4 v[124:127], v[92:93], off offset:3200
	global_load_dwordx4 v[50:53], v[90:91], off offset:448
	global_load_dwordx4 v[128:131], v[92:93], off offset:3264
	global_load_dwordx4 v[54:57], v[90:91], off offset:512
	global_load_dwordx4 v[132:135], v[92:93], off offset:3328
	global_load_dwordx4 v[58:61], v[90:91], off offset:576
	global_load_dwordx4 v[136:139], v[92:93], off offset:3392
	global_load_dwordx4 v[62:65], v[90:91], off offset:640
	global_load_dwordx4 v[140:143], v[92:93], off offset:3456
	global_load_dwordx4 v[66:69], v[90:91], off offset:704
	global_load_dwordx4 v[144:147], v[92:93], off offset:3520
	global_load_dwordx4 v[70:73], v[90:91], off offset:768
	global_load_dwordx4 v[148:151], v[92:93], off offset:3584
	global_load_dwordx4 v[74:77], v[90:91], off offset:832
	global_load_dwordx4 v[152:155], v[92:93], off offset:3648
	global_load_dwordx4 v[78:81], v[90:91], off offset:896
	global_load_dwordx4 v[156:159], v[92:93], off offset:3712
	global_load_dwordx4 v[164:167], v[90:91], off offset:960
	global_load_dwordx4 v[160:163], v[92:93], off offset:3776
	v_lshl_add_u64 v[14:15], v[14:15], 0, s[8:9]
	s_cmpk_gt_u32 s0, 0x3df
	v_lshl_add_u64 v[16:17], v[16:17], 0, s[8:9]
	s_waitcnt vmcnt(30)
	v_mfma_f32_16x16x32_bf16 v[0:3], v[22:25], v[100:103], v[0:3]
	s_waitcnt vmcnt(28)
	v_mfma_f32_16x16x32_bf16 v[0:3], v[26:29], v[104:107], v[0:3]
	s_waitcnt vmcnt(26)
	v_mfma_f32_16x16x32_bf16 v[0:3], v[30:33], v[108:111], v[0:3]
	s_waitcnt vmcnt(24)
	v_mfma_f32_16x16x32_bf16 v[0:3], v[34:37], v[112:115], v[0:3]
	s_waitcnt vmcnt(22)
	v_mfma_f32_16x16x32_bf16 v[0:3], v[38:41], v[116:119], v[0:3]
	s_waitcnt vmcnt(20)
	v_mfma_f32_16x16x32_bf16 v[0:3], v[42:45], v[120:123], v[0:3]
	s_waitcnt vmcnt(18)
	v_mfma_f32_16x16x32_bf16 v[0:3], v[46:49], v[124:127], v[0:3]
	s_waitcnt vmcnt(16)
	v_mfma_f32_16x16x32_bf16 v[0:3], v[50:53], v[128:131], v[0:3]
	s_waitcnt vmcnt(14)
	v_mfma_f32_16x16x32_bf16 v[0:3], v[54:57], v[132:135], v[0:3]
	s_waitcnt vmcnt(12)
	v_mfma_f32_16x16x32_bf16 v[0:3], v[58:61], v[136:139], v[0:3]
	s_waitcnt vmcnt(10)
	v_mfma_f32_16x16x32_bf16 v[0:3], v[62:65], v[140:143], v[0:3]
	s_waitcnt vmcnt(8)
	v_mfma_f32_16x16x32_bf16 v[0:3], v[66:69], v[144:147], v[0:3]
	s_waitcnt vmcnt(6)
	v_mfma_f32_16x16x32_bf16 v[0:3], v[70:73], v[148:151], v[0:3]
	s_waitcnt vmcnt(4)
	v_mfma_f32_16x16x32_bf16 v[0:3], v[74:77], v[152:155], v[0:3]
	s_waitcnt vmcnt(2)
	v_mfma_f32_16x16x32_bf16 v[0:3], v[78:81], v[156:159], v[0:3]
	s_waitcnt vmcnt(0)
	v_mfma_f32_16x16x32_bf16 v[0:3], v[164:167], v[160:163], v[0:3]
	s_cbranch_scc0 .LBB0_909
	global_load_dword v11, v[6:7], off
	v_lshl_or_b32 v14, v18, 4, v19
	v_add_u32_e32 v18, s92, v18
	v_ashrrev_i32_e32 v15, 31, v14
	v_cmp_lt_i32_e64 s[0:1], s10, v18
	v_lshl_add_u64 v[14:15], v[14:15], 1, v[8:9]
	s_or_b64 s[6:7], s[0:1], s[6:7]
	v_add_u32_e32 v10, s2, v10
	s_waitcnt vmcnt(0)
	v_fmamk_f32 v11, v11, 0x3a800000, v20
	v_mul_f32_e32 v16, 0x4b800000, v11
	v_cmp_gt_f32_e32 vcc, s3, v11
	s_nop 1
	v_cndmask_b32_e32 v11, v11, v16, vcc
	v_rsq_f32_e32 v11, v11
	s_nop 0
	v_mul_f32_e32 v16, 0x45800000, v11
	v_cndmask_b32_e32 v11, v11, v16, vcc
	v_mul_f32_e32 v0, v0, v11
	v_mul_f32_e32 v1, v1, v11
	v_mul_f32_e32 v2, v2, v11
	v_mul_f32_e32 v3, v3, v11
	v_max_f32_e32 v0, 0, v0
	v_max_f32_e32 v1, 0, v1
	v_max_f32_e32 v2, 0, v2
	v_max_f32_e32 v3, 0, v3
	v_pk_mul_f32 v[0:1], v[0:1], v[0:1]
	v_pk_mul_f32 v[2:3], v[2:3], v[2:3]
	v_cvt_pk_bf16_f32 v0, v0, v1
	v_cvt_pk_bf16_f32 v1, v2, v3
	global_store_dwordx2 v[14:15], v[0:1], off
	s_andn2_b64 exec, exec, s[6:7]
	s_cbranch_execnz .LBB0_908

; DI unsigned pk2(float a, float b) { f32x2 v = {a, b}; hbf2 r = __builtin_convertvector(v, hbf2); return __builtin_bit_cast(unsigned, r); }
; DI int tid_fresh() { int t = threadIdx.x; asm volatile("" : "+v"(t)); return t; }
; DI float sum_x16_x32(float x) { return sum_x32(sum_x16(x)); }
; DI f32x4 mfma16(bf16x8 a, bf16x8 b, f32x4 c) { return __builtin_amdgcn_mfma_f32_16x16x32_bf16(a, b, c, 0, 0, 0); }
; template <class Epi> DI void small_gemm(const bf16_t* A, const bf16_t* Bt, int N, int K, const Epi& E) {
;     const int tid = tid_fresh(), lane = tid & 63, wid = tid >> 6, fr = lane & 15, fq = lane >> 4;
;     const int nw = gridDim.x * 8;
;     for (int tile = blockIdx.x * 8 + wid; tile < (N >> 4); tile += nw) {
;         const int n0 = tile * 16;
;         f32x4 acc = (f32x4){0.f, 0.f, 0.f, 0.f};
;         const bf16_t* ap = A + (size_t)fr * K + fq * 8;
;         const bf16_t* bp = Bt + (size_t)(n0 + fr) * K + fq * 8;
; #pragma unroll 16
;         for (int k = 0; k < K; k += 32) acc = mfma16(*(const bf16x8*)(bp + k), *(const bf16x8*)(ap + k), acc);
;         E(acc, fr, n0 + fq * 4, fq);
;     }
; }
;     DI void operator()(f32x4 acc, int row, int n, int fq) const {
;         const size_t r = (size_t)(MR + row);
;         const f32x4 rv = MODE == 0 ? *(const f32x4*)(meta + (size_t)row * 1024 + n) : *(const f32x4*)(h + r * 1024 + n);
;         const f32x4 v = acc + rv;
;         *(f32x4*)(h + r * 1024 + n) = v;
;         u32x2 w; w.x = pk2(v[0], v[1]); w.y = pk2(v[2], v[3]);
;         *(u32x2*)(hb + r * 1024 + n) = w;
;         float sq = v[0] * v[0] + v[1] * v[1] + v[2] * v[2] + v[3] * v[3];
;         sq = sum_x16_x32(sq);
;         if (fq == 0) atomicAdd(ss + r, sq);
;     }
.LBB0_987:
	v_lshl_add_u64 v[22:23], v[16:17], 0, v[4:5]
	v_add_co_u32_e32 v90, vcc, 0x1800000, v22
	v_lshl_add_u64 v[24:25], v[18:19], 0, v[4:5]
	s_nop 0
	v_addc_co_u32_e32 v91, vcc, 0, v23, vcc
	v_add_co_u32_e32 v92, vcc, 0x1fc47000, v24
	s_addk_i32 s3, 0x200
	s_nop 0
	v_addc_co_u32_e32 v93, vcc, 0, v25, vcc
	global_load_dwordx4 v[22:25], v[90:91], off
	global_load_dwordx4 v[100:103], v[92:93], off offset:2816
	global_load_dwordx4 v[26:29], v[90:91], off offset:64
	global_load_dwordx4 v[104:107], v[92:93], off offset:2880
	global_load_dwordx4 v[30:33], v[90:91], off offset:128
	global_load_dwordx4 v[108:111], v[92:93], off offset:2944
	global_load_dwordx4 v[34:37], v[90:91], off offset:192
	global_load_dwordx4 v[112:115], v[92:93], off offset:3008
	global_load_dwordx4 v[38:41], v[90:91], off offset:256
	global_load_dwordx4 v[116:119], v[92:93], off offset:3072
	global_load_dwordx4 v[42:45], v[90:91], off offset:320
	global_load_dwordx4 v[120:123], v[92:93], off offset:3136
	global_load_dwordx4 v[46:49], v[90:91], off offset:384
	global_load_dwordx4 v[124:127], v[92:93], off offset:3200
	global_load_dwordx4 v[50:53], v[90:91], off offset:448
	global_load_dwordx4 v[128:131], v[92:93], off offset:3264
	global_load_dwordx4 v[54:57], v[90:91], off offset:512
	global_load_dwordx4 v[132:135], v[92:93], off offset:3328
	global_load_dwordx4 v[58:61], v[90:91], off offset:576
	global_load_dwordx4 v[136:139], v[92:93], off offset:3392
	global_load_dwordx4 v[62:65], v[90:91], off offset:640
	global_load_dwordx4 v[140:143], v[92:93], off offset:3456
	global_load_dwordx4 v[66:69], v[90:91], off offset:704
	global_load_dwordx4 v[144:147], v[92:93], off offset:3520
	global_load_dwordx4 v[70:73], v[90:91], off offset:768
	global_load_dwordx4 v[148:151], v[92:93], off offset:3584
	global_load_dwordx4 v[74:77], v[90:91], off offset:832
	global_load_dwordx4 v[152:155], v[92:93], off offset:3648
	global_load_dwordx4 v[78:81], v[90:91], off offset:896
	global_load_dwordx4 v[156:159], v[92:93], off offset:3712
	global_load_dwordx4 v[164:167], v[90:91], off offset:960
	global_load_dwordx4 v[160:163], v[92:93], off offset:3776
	v_lshl_add_u64 v[16:17], v[16:17], 0, s[8:9]
	s_cmpk_gt_u32 s3, 0xfdf
	v_lshl_add_u64 v[18:19], v[18:19], 0, s[8:9]
	s_waitcnt vmcnt(30)
	v_mfma_f32_16x16x32_bf16 v[0:3], v[22:25], v[100:103], v[0:3]
	s_waitcnt vmcnt(28)
	v_mfma_f32_16x16x32_bf16 v[0:3], v[26:29], v[104:107], v[0:3]
	s_waitcnt vmcnt(26)
	v_mfma_f32_16x16x32_bf16 v[0:3], v[30:33], v[108:111], v[0:3]
	s_waitcnt vmcnt(24)
	v_mfma_f32_16x16x32_bf16 v[0:3], v[34:37], v[112:115], v[0:3]
	s_waitcnt vmcnt(22)
	v_mfma_f32_16x16x32_bf16 v[0:3], v[38:41], v[116:119], v[0:3]
	s_waitcnt vmcnt(20)
	v_mfma_f32_16x16x32_bf16 v[0:3], v[42:45], v[120:123], v[0:3]
	s_waitcnt vmcnt(18)
	v_mfma_f32_16x16x32_bf16 v[0:3], v[46:49], v[124:127], v[0:3]
	s_waitcnt vmcnt(16)
	v_mfma_f32_16x16x32_bf16 v[0:3], v[50:53], v[128:131], v[0:3]
	s_waitcnt vmcnt(14)
	v_mfma_f32_16x16x32_bf16 v[0:3], v[54:57], v[132:135], v[0:3]
	s_waitcnt vmcnt(12)
	v_mfma_f32_16x16x32_bf16 v[0:3], v[58:61], v[136:139], v[0:3]
	s_waitcnt vmcnt(10)
	v_mfma_f32_16x16x32_bf16 v[0:3], v[62:65], v[140:143], v[0:3]
	s_waitcnt vmcnt(8)
	v_mfma_f32_16x16x32_bf16 v[0:3], v[66:69], v[144:147], v[0:3]
	s_waitcnt vmcnt(6)
	v_mfma_f32_16x16x32_bf16 v[0:3], v[70:73], v[148:151], v[0:3]
	s_waitcnt vmcnt(4)
	v_mfma_f32_16x16x32_bf16 v[0:3], v[74:77], v[152:155], v[0:3]
	s_waitcnt vmcnt(2)
	v_mfma_f32_16x16x32_bf16 v[0:3], v[78:81], v[156:159], v[0:3]
	s_waitcnt vmcnt(0)
	v_mfma_f32_16x16x32_bf16 v[0:3], v[164:167], v[160:163], v[0:3]
	s_cbranch_scc0 .LBB0_987
	v_lshl_or_b32 v22, v20, 4, v21
	v_ashrrev_i32_e32 v23, 31, v22
	v_lshl_add_u64 v[24:25], v[22:23], 2, v[6:7]
	global_load_dwordx4 v[16:19], v[24:25], off
	v_lshl_add_u64 v[22:23], v[22:23], 1, v[8:9]
	s_waitcnt vmcnt(0)
	s_nop 0
	v_pk_add_f32 v[2:3], v[2:3], v[18:19]
	v_pk_add_f32 v[0:1], v[0:1], v[16:17]
	global_store_dwordx4 v[24:25], v[0:3], off
	v_cvt_pk_bf16_f32 v16, v0, v1
	v_cvt_pk_bf16_f32 v17, v2, v3
	v_mul_f32_e32 v1, v1, v1
	v_fmac_f32_e32 v1, v0, v0
	v_fmac_f32_e32 v1, v2, v2
	v_fmac_f32_e32 v1, v3, v3
	v_mov_b32_e32 v0, v1
	s_nop 1
	v_permlane16_swap_b32_e32 v1, v0
	v_add_f32_e32 v0, v1, v0
	v_mov_b32_e32 v1, v0
	s_nop 1
	v_permlane32_swap_b32_e32 v0, v1
	global_store_dwordx2 v[22:23], v[16:17], off
	s_and_saveexec_b64 s[10:11], s[0:1]
	s_cbranch_execz .LBB0_985
	v_add_f32_e32 v0, v0, v1
	global_atomic_add_f32 v[10:11], v0, off
	s_branch .LBB0_985

; DI unsigned pk2(float a, float b) { f32x2 v = {a, b}; hbf2 r = __builtin_convertvector(v, hbf2); return __builtin_bit_cast(unsigned, r); }
; DI bf16_t f2bf(float a) { return (bf16_t)(pk2(a, 0.f) & 0xffffu); }
; DI int tid_fresh() { int t = threadIdx.x; asm volatile("" : "+v"(t)); return t; }
; DI f32x4 mfma16(bf16x8 a, bf16x8 b, f32x4 c) { return __builtin_amdgcn_mfma_f32_16x16x32_bf16(a, b, c, 0, 0, 0); }
; template <class Epi> DI void small_gemm(const bf16_t* A, const bf16_t* Bt, int N, int K, const Epi& E) {
;     const int tid = tid_fresh(), lane = tid & 63, wid = tid >> 6, fr = lane & 15, fq = lane >> 4;
;     const int nw = gridDim.x * 8;
;     for (int tile = blockIdx.x * 8 + wid; tile < (N >> 4); tile += nw) {
;         const int n0 = tile * 16;
;         f32x4 acc = (f32x4){0.f, 0.f, 0.f, 0.f};
;         const bf16_t* ap = A + (size_t)fr * K + fq * 8;
;         const bf16_t* bp = Bt + (size_t)(n0 + fr) * K + fq * 8;
; #pragma unroll 16
;         for (int k = 0; k < K; k += 32) acc = mfma16(*(const bf16x8*)(bp + k), *(const bf16x8*)(ap + k), acc);
;         E(acc, fr, n0 + fq * 4, fq);
;     }
; }
;     DI void operator()(f32x4 v, int row, int n, int fq) const {
;         const size_t r = (size_t)(MR + row);
;         const float rstd = rsqrtf(ss[r] * (1.0f / 1024.0f) + EPS);
; #pragma unroll
;         for (int j = 0; j < 4; ++j) v[j] *= rstd;
;         if (n < 2048) {
;             if (((n - fq * 4) & 63) == 0) {
;                 const f32x4 cs = *(const f32x4*)(rope + row * 16 + (fq & 1) * 4), sn = *(const f32x4*)(rope + row * 16 + 8 + (fq & 1) * 4);
; #pragma unroll
;                 for (int j = 0; j < 4; ++j) {
;                     const float other = __shfl_xor(v[j], 32);
;                     v[j] = fq < 2 ? v[j] * cs[j] - other * sn[j] : v[j] * cs[j] + other * sn[j];
;                 }
;             }
;             u32x2 w; w.x = pk2(v[0], v[1]); w.y = pk2(v[2], v[3]);
;             *(u32x2*)(QK + r * 2048 + n) = w;
;         } else {
; #pragma unroll
;             for (int j = 0; j < 4; ++j) VT[(size_t)(n - 2048 + j) * MP + MR + ((row & 3) | ((row & 4) << 1) | ((row & 8) >> 1))] = f2bf(v[j]);
;         }
;     }
.LBB0_1085:
	v_lshl_add_u64 v[26:27], v[18:19], 0, v[8:9]
	v_add_co_u32_e32 v94, vcc, 0x2000000, v26
	v_lshl_add_u64 v[28:29], v[20:21], 0, v[8:9]
	s_nop 0
	v_addc_co_u32_e32 v95, vcc, 0, v27, vcc
	v_add_co_u32_e32 v96, vcc, 0x7ac7000, v28
	s_addk_i32 s10, 0x200
	s_nop 0
	v_addc_co_u32_e32 v97, vcc, 0, v29, vcc
	global_load_dwordx4 v[26:29], v[94:95], off
	global_load_dwordx4 v[100:103], v[96:97], off offset:2816
	global_load_dwordx4 v[30:33], v[94:95], off offset:64
	global_load_dwordx4 v[104:107], v[96:97], off offset:2880
	global_load_dwordx4 v[34:37], v[94:95], off offset:128
	global_load_dwordx4 v[108:111], v[96:97], off offset:2944
	global_load_dwordx4 v[38:41], v[94:95], off offset:192
	global_load_dwordx4 v[112:115], v[96:97], off offset:3008
	global_load_dwordx4 v[42:45], v[94:95], off offset:256
	global_load_dwordx4 v[116:119], v[96:97], off offset:3072
	global_load_dwordx4 v[46:49], v[94:95], off offset:320
	global_load_dwordx4 v[120:123], v[96:97], off offset:3136
	global_load_dwordx4 v[50:53], v[94:95], off offset:384
	global_load_dwordx4 v[124:127], v[96:97], off offset:3200
	global_load_dwordx4 v[54:57], v[94:95], off offset:448
	global_load_dwordx4 v[128:131], v[96:97], off offset:3264
	global_load_dwordx4 v[58:61], v[94:95], off offset:512
	global_load_dwordx4 v[132:135], v[96:97], off offset:3328
	global_load_dwordx4 v[62:65], v[94:95], off offset:576
	global_load_dwordx4 v[136:139], v[96:97], off offset:3392
	global_load_dwordx4 v[66:69], v[94:95], off offset:640
	global_load_dwordx4 v[140:143], v[96:97], off offset:3456
	global_load_dwordx4 v[70:73], v[94:95], off offset:704
	global_load_dwordx4 v[144:147], v[96:97], off offset:3520
	global_load_dwordx4 v[74:77], v[94:95], off offset:768
	global_load_dwordx4 v[148:151], v[96:97], off offset:3584
	global_load_dwordx4 v[78:81], v[94:95], off offset:832
	global_load_dwordx4 v[152:155], v[96:97], off offset:3648
	global_load_dwordx4 v[82:85], v[94:95], off offset:896
	global_load_dwordx4 v[156:159], v[96:97], off offset:3712
	global_load_dwordx4 v[164:167], v[94:95], off offset:960
	global_load_dwordx4 v[160:163], v[96:97], off offset:3776
	v_lshl_add_u64 v[18:19], v[18:19], 0, s[8:9]
	s_cmpk_gt_u32 s10, 0x3df
	v_lshl_add_u64 v[20:21], v[20:21], 0, s[8:9]
	s_waitcnt vmcnt(30)
	v_mfma_f32_16x16x32_bf16 v[0:3], v[26:29], v[100:103], v[0:3]
	s_waitcnt vmcnt(28)
	v_mfma_f32_16x16x32_bf16 v[0:3], v[30:33], v[104:107], v[0:3]
	s_waitcnt vmcnt(26)
	v_mfma_f32_16x16x32_bf16 v[0:3], v[34:37], v[108:111], v[0:3]
	s_waitcnt vmcnt(24)
	v_mfma_f32_16x16x32_bf16 v[0:3], v[38:41], v[112:115], v[0:3]
	s_waitcnt vmcnt(22)
	v_mfma_f32_16x16x32_bf16 v[0:3], v[42:45], v[116:119], v[0:3]
	s_waitcnt vmcnt(20)
	v_mfma_f32_16x16x32_bf16 v[0:3], v[46:49], v[120:123], v[0:3]
	s_waitcnt vmcnt(18)
	v_mfma_f32_16x16x32_bf16 v[0:3], v[50:53], v[124:127], v[0:3]
	s_waitcnt vmcnt(16)
	v_mfma_f32_16x16x32_bf16 v[0:3], v[54:57], v[128:131], v[0:3]
	s_waitcnt vmcnt(14)
	v_mfma_f32_16x16x32_bf16 v[0:3], v[58:61], v[132:135], v[0:3]
	s_waitcnt vmcnt(12)
	v_mfma_f32_16x16x32_bf16 v[0:3], v[62:65], v[136:139], v[0:3]
	s_waitcnt vmcnt(10)
	v_mfma_f32_16x16x32_bf16 v[0:3], v[66:69], v[140:143], v[0:3]
	s_waitcnt vmcnt(8)
	v_mfma_f32_16x16x32_bf16 v[0:3], v[70:73], v[144:147], v[0:3]
	s_waitcnt vmcnt(6)
	v_mfma_f32_16x16x32_bf16 v[0:3], v[74:77], v[148:151], v[0:3]
	s_waitcnt vmcnt(4)
	v_mfma_f32_16x16x32_bf16 v[0:3], v[78:81], v[152:155], v[0:3]
	s_waitcnt vmcnt(2)
	v_mfma_f32_16x16x32_bf16 v[0:3], v[82:85], v[156:159], v[0:3]
	s_waitcnt vmcnt(0)
	v_mfma_f32_16x16x32_bf16 v[0:3], v[164:167], v[160:163], v[0:3]
	s_cbranch_scc0 .LBB0_1085
	global_load_dword v15, v[6:7], off
	s_waitcnt vmcnt(0)
	v_fmamk_f32 v15, v15, 0x3a800000, v24
	v_mul_f32_e32 v18, 0x4b800000, v15
	v_cmp_gt_f32_e32 vcc, s3, v15
	s_nop 1
	v_cndmask_b32_e32 v15, v15, v18, vcc
	v_rsq_f32_e32 v15, v15
	v_lshl_or_b32 v18, v22, 4, v23
	v_mul_f32_e32 v19, 0x45800000, v15
	v_cndmask_b32_e32 v26, v15, v19, vcc
	v_pk_mul_f32 v[20:21], v[0:1], v[26:27] op_sel_hi:[1,0]
	v_pk_mul_f32 v[0:1], v[2:3], v[26:27] op_sel_hi:[1,0]
	v_cmp_lt_i32_e32 vcc, s14, v18
	s_and_saveexec_b64 s[10:11], vcc
	s_xor_b64 s[10:11], exec, s[10:11]
	s_cbranch_execz .LBB0_1088
	v_add_u32_e32 v15, 0xfffff800, v18
	v_mov_b64_e32 v[2:3], s[74:75]
	v_mad_u64_u32 v[26:27], s[12:13], v15, s15, v[2:3]
	v_lshl_add_u64 v[26:27], v[26:27], 0, v[4:5]
	v_add_co_u32_e32 v26, vcc, 0x10000, v26
	v_cvt_pk_bf16_f32 v19, v20, s0
	s_nop 0
	v_addc_co_u32_e32 v27, vcc, 0, v27, vcc
	global_store_short v[26:27], v19, off
	v_add_u32_e32 v19, 0xfffff801, v18
	v_cvt_pk_bf16_f32 v15, v21, s0
	v_mad_u64_u32 v[20:21], s[12:13], v19, s15, v[2:3]
	v_lshl_add_u64 v[20:21], v[20:21], 0, v[4:5]
	v_add_co_u32_e32 v20, vcc, 0x10000, v20
	v_cvt_pk_bf16_f32 v0, v0, s0
	s_nop 0
	v_addc_co_u32_e32 v21, vcc, 0, v21, vcc
	global_store_short v[20:21], v15, off
	v_add_u32_e32 v15, 0xfffff802, v18
	v_mad_u64_u32 v[20:21], s[12:13], v15, s15, v[2:3]
	v_lshl_add_u64 v[20:21], v[20:21], 0, v[4:5]
	v_add_co_u32_e32 v20, vcc, 0x10000, v20
	v_cvt_pk_bf16_f32 v15, v1, s0
	s_nop 0
	v_addc_co_u32_e32 v21, vcc, 0, v21, vcc
	global_store_short v[20:21], v0, off
	v_add_u32_e32 v0, 0xfffff803, v18
	v_mad_u64_u32 v[0:1], s[12:13], v0, s15, v[2:3]
	v_lshl_add_u64 v[0:1], v[0:1], 0, v[4:5]
	v_add_co_u32_e32 v0, vcc, 0x10000, v0
	s_nop 1
	v_addc_co_u32_e32 v1, vcc, 0, v1, vcc
	global_store_short v[0:1], v15, off
